# P2: sixteen workgroup groups (cid bits 3-6) each start at a different one of their 16 items (rotated visiting order)
# speedup vs baseline: 1.0190x; 1.0020x over previous
.LBB0_536:
	v_readlane_b32 s0, v246, 4
	s_cmp_lt_i32 s0, 3
	v_readlane_b32 s1, v246, 5
	s_cselect_b64 s[4:5], -1, 0
	s_and_b64 s[0:1], s[4:5], s[2:3]
	s_xor_b64 s[0:1], s[0:1], -1
	s_cmpk_gt_i32 s30, 0xfff
	s_cselect_b64 s[2:3], -1, 0
	s_or_b64 s[0:1], s[2:3], s[0:1]
	s_and_b64 vcc, exec, s[0:1]
	v_writelane_b32 v246, s20, 62
	s_nop 1
	v_writelane_b32 v245, s22, 0
	v_writelane_b32 v246, s21, 63
	v_writelane_b32 v245, s23, 1
	s_cbranch_vccnz .LBB0_577
	v_writelane_b32 v245, s4, 2
	v_cmp_gt_u32_e64 s[0:1], 64, v202
	v_and_b32_e32 v40, 63, v202
	v_writelane_b32 v245, s5, 3
	v_writelane_b32 v245, s0, 4
	v_lshrrev_b32_e32 v44, 3, v202
	v_and_b32_e32 v16, 7, v202
	v_readlane_b32 s5, v246, 0
	v_writelane_b32 v245, s1, 5
	v_sub_co_u32_e64 v2, s[0:1], v44, v16
	v_lshlrev_b32_e32 v4, 2, v40
	v_cvt_f32_u32_e32 v134, v2
	v_add_u32_e32 v137, s5, v4
	v_and_b32_e32 v2, 0x3c0, v202
	v_lshl_add_u32 v138, v2, 2, v137
	v_xor_b32_e32 v2, 0x7f, v44
	v_cvt_f32_u32_e32 v142, v2
	v_add_u32_e32 v2, 0x200, v202
	v_bfe_u32 v17, v202, 4, 2
	v_lshrrev_b32_e32 v0, 4, v202
	v_mov_b32_e32 v1, 0xfffe2000
	v_lshrrev_b32_e32 v46, 3, v2
	v_lshlrev_b32_e32 v42, 3, v17
	v_bfe_u32 v18, v202, 2, 2
	v_and_or_b32 v41, v0, 60, v1
	v_mov_b32_e32 v1, s5
	s_movk_i32 s6, 0x90
	v_sub_u32_e32 v2, 0x7f, v46
	v_or_b32_e32 v6, v42, v18
	v_lshrrev_b32_e32 v9, 5, v202
	v_cvt_f32_i32_e32 v144, v2
	v_and_b32_e32 v5, 15, v202
	v_lshrrev_b32_e32 v2, 7, v202
	v_mad_u32_u24 v8, v6, s6, v1
	v_and_b32_e32 v10, 2, v9
	v_writelane_b32 v245, s0, 6
	v_lshl_add_u32 v7, v2, 5, v8
	v_lshlrev_b32_e32 v9, 5, v10
	v_lshlrev_b32_e32 v2, 10, v2
	v_lshlrev_b32_e32 v11, 8, v17
	v_lshl_or_b32 v10, v10, 4, v5
	v_writelane_b32 v245, s1, 7
	v_or3_b32 v48, v11, v2, v10
	s_movk_i32 s0, 0x80
	v_lshrrev_b32_e32 v15, 2, v202
	v_and_b32_e32 v2, 8, v202
	v_cmp_gt_u32_e64 s[0:1], s0, v202
	v_and_or_b32 v2, v15, 16, v2
	v_lshrrev_b32_e32 v146, 3, v2
	v_writelane_b32 v245, s0, 8
	v_lshlrev_b32_e32 v2, 2, v17
	v_or_b32_e32 v13, 2, v2
	v_writelane_b32 v245, s1, 9
	v_cmp_gt_u32_e64 s[0:1], v2, v16
	v_or_b32_e32 v12, 0x80, v16
	v_and_b32_e32 v19, 0xe0, v15
	v_writelane_b32 v245, s0, 10
	v_mad_u32_u24 v11, v5, s6, v1
	v_or_b32_e32 v147, v2, v19
	v_writelane_b32 v245, s1, 11
	v_cmp_lt_u32_e64 s[0:1], v2, v16
	v_or_b32_e32 v149, 2, v147
	v_or_b32_e32 v150, 3, v147
	v_writelane_b32 v245, s0, 12
	v_or_b32_e32 v151, 16, v147
	v_or_b32_e32 v152, 17, v147
	v_writelane_b32 v245, s1, 13
	v_cmp_gt_u32_e64 s[0:1], v13, v16
	v_or_b32_e32 v13, 3, v2
	v_or_b32_e32 v153, 18, v147
	v_writelane_b32 v245, s0, 14
	v_or_b32_e32 v154, 19, v147
	v_add_u32_e32 v155, 32, v147
	v_writelane_b32 v245, s1, 15
	v_cmp_gt_u32_e64 s[0:1], v13, v16
	v_or_b32_e32 v13, 0x81, v2
	v_add_u32_e32 v156, 33, v147
	v_writelane_b32 v245, s0, 16
	v_add_u32_e32 v157, 34, v147
	v_add_u32_e32 v158, 35, v147
	v_writelane_b32 v245, s1, 17
	v_cmp_gt_u32_e64 s[0:1], v13, v12
	v_or_b32_e32 v13, 0x82, v2
	v_add_u32_e32 v159, 48, v147
	v_writelane_b32 v245, s0, 18
	v_add_u32_e32 v160, 49, v147
	v_add_u32_e32 v161, 50, v147
	v_writelane_b32 v245, s1, 19
	v_cmp_gt_u32_e64 s[0:1], v13, v12
	v_or_b32_e32 v13, 0x83, v2
	v_add_u32_e32 v162, 51, v147
	v_writelane_b32 v245, s0, 20
	v_add_u32_e32 v163, 64, v147
	v_add_u32_e32 v164, 0x41, v147
	v_writelane_b32 v245, s1, 21
	v_cmp_gt_u32_e64 s[0:1], v13, v12
	v_add_u32_e32 v165, 0x42, v147
	v_add_u32_e32 v166, 0x43, v147
	v_writelane_b32 v245, s0, 22
	v_add_u32_e32 v167, 0x50, v147
	s_waitcnt vmcnt(0)
	v_add_u32_e32 v168, 0x51, v147
	v_writelane_b32 v245, s1, 23
	s_movk_i32 s0, 0x1ff
	v_cmp_lt_u32_e64 s[0:1], s0, v202
	v_add_u32_e32 v169, 0x52, v147
	v_add_u32_e32 v170, 0x53, v147
	v_writelane_b32 v245, s0, 24
	v_add_u32_e32 v171, 0x60, v147
	v_add_u32_e32 v172, 0x61, v147
	v_writelane_b32 v245, s1, 25
	s_movk_i32 s0, 0xf0
	v_and_or_b32 v54, v15, s0, v5
	v_or_b32_e32 v5, v19, v5
	v_mad_u32_u24 v15, v5, s6, v1
	v_add_u32_e32 v5, 0x80, v54
	v_cmp_gt_u32_e32 vcc, v147, v54
	v_cmp_le_u32_e64 s[0:1], v147, v5
	s_and_b64 s[0:1], vcc, s[0:1]
	v_cmp_ge_u32_e32 vcc, v147, v54
	v_writelane_b32 v245, s0, 26
	v_add_u32_e32 v173, 0x62, v147
	v_add_u32_e32 v174, 0x63, v147
	v_writelane_b32 v245, s1, 27
	v_cmp_lt_u32_e64 s[0:1], v147, v5
	s_and_b64 s[0:1], vcc, s[0:1]
	v_cmp_gt_u32_e32 vcc, v149, v54
	v_writelane_b32 v245, s0, 28
	v_add_u32_e32 v175, 0x70, v147
	v_add_u32_e32 v176, 0x71, v147
	v_writelane_b32 v245, s1, 29
	v_cmp_le_u32_e64 s[0:1], v149, v5
	s_and_b64 s[0:1], vcc, s[0:1]
	v_cmp_gt_u32_e32 vcc, v150, v54
	v_writelane_b32 v245, s0, 30
	v_add_u32_e32 v177, 0x72, v147
	v_add_u32_e32 v178, 0x73, v147
	v_writelane_b32 v245, s1, 31
	v_cmp_le_u32_e64 s[0:1], v150, v5
	s_and_b64 s[0:1], vcc, s[0:1]
	v_cmp_gt_u32_e32 vcc, v151, v54
	v_writelane_b32 v245, s0, 32
	v_add_u32_e32 v19, 0x80, v147
	s_mov_b64 s[16:17], s[20:21]
	v_writelane_b32 v245, s1, 33
	v_cmp_le_u32_e64 s[0:1], v151, v5
	s_and_b64 s[0:1], vcc, s[0:1]
	v_cmp_gt_u32_e32 vcc, v152, v54
	v_writelane_b32 v245, s0, 34
	s_mov_b64 s[18:19], s[22:23]
	v_mov_b32_e32 v43, 0
	v_writelane_b32 v245, s1, 35
	v_cmp_le_u32_e64 s[0:1], v152, v5
	s_and_b64 s[0:1], vcc, s[0:1]
	v_cmp_gt_u32_e32 vcc, v153, v54
	v_writelane_b32 v245, s0, 36
	v_readlane_b32 s44, v246, 6
	v_or_b32_e32 v12, v2, v18
	v_writelane_b32 v245, s1, 37
	v_cmp_le_u32_e64 s[0:1], v153, v5
	s_and_b64 s[0:1], vcc, s[0:1]
	v_cmp_gt_u32_e32 vcc, v154, v54
	v_writelane_b32 v245, s0, 38
	v_readlane_b32 s45, v246, 7
	v_readlane_b32 s46, v246, 8
	v_writelane_b32 v245, s1, 39
	v_cmp_le_u32_e64 s[0:1], v154, v5
	s_and_b64 s[0:1], vcc, s[0:1]
	v_cmp_gt_u32_e32 vcc, v155, v54
	v_writelane_b32 v245, s0, 40
	v_readlane_b32 s47, v246, 9
	v_readlane_b32 s48, v246, 10
	v_writelane_b32 v245, s1, 41
	v_cmp_le_u32_e64 s[0:1], v155, v5
	s_and_b64 s[0:1], vcc, s[0:1]
	v_cmp_gt_u32_e32 vcc, v156, v54
	v_writelane_b32 v245, s0, 42
	v_readlane_b32 s49, v246, 11
	v_readlane_b32 s50, v246, 12
	v_writelane_b32 v245, s1, 43
	v_cmp_le_u32_e64 s[0:1], v156, v5
	s_and_b64 s[0:1], vcc, s[0:1]
	v_cmp_gt_u32_e32 vcc, v157, v54
	v_writelane_b32 v245, s0, 44
	v_readlane_b32 s51, v246, 13
	v_readlane_b32 s52, v246, 14
	v_writelane_b32 v245, s1, 45
	v_cmp_le_u32_e64 s[0:1], v157, v5
	s_and_b64 s[0:1], vcc, s[0:1]
	v_cmp_gt_u32_e32 vcc, v158, v54
	v_writelane_b32 v245, s0, 46
	v_readlane_b32 s53, v246, 15
	v_readlane_b32 s54, v246, 16
	v_writelane_b32 v245, s1, 47
	v_cmp_le_u32_e64 s[0:1], v158, v5
	s_and_b64 s[0:1], vcc, s[0:1]
	v_cmp_gt_u32_e32 vcc, v159, v54
	v_writelane_b32 v245, s0, 48
	v_readlane_b32 s55, v246, 17
	v_readlane_b32 s56, v246, 18
	v_writelane_b32 v245, s1, 49
	v_cmp_le_u32_e64 s[0:1], v159, v5
	s_and_b64 s[0:1], vcc, s[0:1]
	v_cmp_gt_u32_e32 vcc, v160, v54
	v_writelane_b32 v245, s0, 50
	v_readlane_b32 s57, v246, 19
	v_readlane_b32 s58, v246, 20
	v_writelane_b32 v245, s1, 51
	v_cmp_le_u32_e64 s[0:1], v160, v5
	s_and_b64 s[0:1], vcc, s[0:1]
	v_cmp_gt_u32_e32 vcc, v161, v54
	v_writelane_b32 v245, s0, 52
	v_readlane_b32 s59, v246, 21
	v_lshlrev_b32_e32 v20, 3, v40
	v_writelane_b32 v245, s1, 53
	v_cmp_le_u32_e64 s[0:1], v161, v5
	s_and_b64 s[0:1], vcc, s[0:1]
	v_cmp_gt_u32_e32 vcc, v162, v54
	v_writelane_b32 v245, s0, 54
	s_waitcnt lgkmcnt(0)
	v_mov_b32_e32 v21, v43
	v_lshrrev_b32_e32 v0, 6, v202
	v_writelane_b32 v245, s1, 55
	v_cmp_le_u32_e64 s[0:1], v162, v5
	s_and_b64 s[0:1], vcc, s[0:1]
	v_cmp_gt_u32_e32 vcc, v163, v54
	v_writelane_b32 v245, s0, 56
	v_or_b32_e32 v45, 0x8000, v0
	v_lshlrev_b32_e32 v135, 9, v0
	v_writelane_b32 v245, s1, 57
	v_cmp_le_u32_e64 s[0:1], v163, v5
	s_and_b64 s[0:1], vcc, s[0:1]
	v_cmp_gt_u32_e32 vcc, v164, v54
	v_writelane_b32 v245, s0, 58
	v_lshl_add_u32 v136, v0, 5, s5
	v_lshlrev_b32_e32 v3, 11, v0
	v_writelane_b32 v245, s1, 59
	v_cmp_le_u32_e64 s[0:1], v164, v5
	s_and_b64 s[0:1], vcc, s[0:1]
	v_cmp_gt_u32_e32 vcc, v165, v54
	v_writelane_b32 v245, s0, 60
	v_add_u32_e32 v0, 1, v0
	v_cvt_f32_u32_e32 v139, v0
	v_writelane_b32 v245, s1, 61
	v_cmp_le_u32_e64 s[0:1], v165, v5
	s_and_b64 s[0:1], vcc, s[0:1]
	v_cmp_gt_u32_e32 vcc, v166, v54
	v_writelane_b32 v245, s0, 62
	v_lshlrev_b32_e32 v0, 4, v16
	v_mad_u32_u24 v12, v12, s6, v1
	v_writelane_b32 v245, s1, 63
	v_cmp_le_u32_e64 s[0:1], v166, v5
	s_and_b64 s[0:1], vcc, s[0:1]
	v_cmp_gt_u32_e32 vcc, v167, v54
	v_writelane_b32 v244, s0, 0
	v_add_u32_e32 v141, s5, v0
	v_lshlrev_b32_e32 v6, 3, v202
	v_writelane_b32 v244, s1, 1
	v_cmp_le_u32_e64 s[0:1], v167, v5
	s_and_b64 s[0:1], vcc, s[0:1]
	v_cmp_gt_u32_e32 vcc, v168, v54
	v_writelane_b32 v244, s0, 2
	v_add_u32_e32 v14, 0x600, v202
	v_and_b32_e32 v6, 24, v6
	v_writelane_b32 v244, s1, 3
	v_cmp_le_u32_e64 s[0:1], v168, v5
	s_and_b64 s[0:1], vcc, s[0:1]
	v_cmp_gt_u32_e32 vcc, v169, v54
	v_writelane_b32 v244, s0, 4
	v_or_b32_e32 v50, 0x80, v44
	v_lshrrev_b32_e32 v52, 3, v14
	v_writelane_b32 v244, s1, 5
	v_cmp_le_u32_e64 s[0:1], v169, v5
	s_and_b64 s[0:1], vcc, s[0:1]
	v_cmp_gt_u32_e32 vcc, v170, v54
	v_writelane_b32 v244, s0, 6
	v_lshl_add_u32 v133, v16, 8, s5
	v_lshlrev_b32_e32 v140, 3, v16
	v_writelane_b32 v244, s1, 7
	v_cmp_le_u32_e64 s[0:1], v170, v5
	s_and_b64 s[0:1], vcc, s[0:1]
	v_cmp_gt_u32_e32 vcc, v171, v54
	v_writelane_b32 v244, s0, 8
	v_add_u32_e32 v8, v8, v6
	v_and_b32_e32 v10, 48, v202
	v_writelane_b32 v244, s1, 9
	v_cmp_le_u32_e64 s[0:1], v171, v5
	s_and_b64 s[0:1], vcc, s[0:1]
	v_cmp_gt_u32_e32 vcc, v172, v54
	v_writelane_b32 v244, s0, 10
	v_mul_u32_u24_e32 v13, 0x90, v50
	v_mul_u32_u24_e32 v14, 0x90, v52
	v_writelane_b32 v244, s1, 11
	v_cmp_le_u32_e64 s[0:1], v172, v5
	s_and_b64 s[0:1], vcc, s[0:1]
	v_cmp_gt_u32_e32 vcc, v173, v54
	v_writelane_b32 v244, s0, 12
	v_lshl_add_u32 v55, v202, 2, s5
	v_lshl_add_u32 v132, v44, 8, s5
	v_writelane_b32 v244, s1, 13
	v_cmp_le_u32_e64 s[0:1], v173, v5
	s_and_b64 s[0:1], vcc, s[0:1]
	v_cmp_gt_u32_e32 vcc, v174, v54
	v_writelane_b32 v244, s0, 14
	v_mul_u32_u24_e32 v143, 0x90, v44
	v_mul_u32_u24_e32 v145, 0x90, v46
	v_writelane_b32 v244, s1, 15
	v_cmp_le_u32_e64 s[0:1], v174, v5
	s_and_b64 s[0:1], vcc, s[0:1]
	v_cmp_gt_u32_e32 vcc, v175, v54
	v_writelane_b32 v244, s0, 16
	v_mov_b32_e32 v49, v43
	v_mov_b32_e32 v47, v43
	v_writelane_b32 v244, s1, 17
	v_cmp_le_u32_e64 s[0:1], v175, v5
	s_and_b64 s[0:1], vcc, s[0:1]
	v_cmp_gt_u32_e32 vcc, v176, v54
	v_writelane_b32 v244, s0, 18
	v_mov_b32_e32 v51, v43
	v_mov_b32_e32 v53, v43
	v_writelane_b32 v244, s1, 19
	v_cmp_le_u32_e64 s[0:1], v176, v5
	s_and_b64 s[0:1], vcc, s[0:1]
	v_cmp_gt_u32_e32 vcc, v177, v54
	v_writelane_b32 v244, s0, 20
	v_or_b32_e32 v148, 1, v147
	v_or_b32_e32 v179, 0x8000, v16
	v_writelane_b32 v244, s1, 21
	v_cmp_le_u32_e64 s[0:1], v177, v5
	s_and_b64 s[0:1], vcc, s[0:1]
	v_cmp_gt_u32_e32 vcc, v178, v54
	v_writelane_b32 v244, s0, 22
	v_or_b32_e32 v78, 16, v48
	v_mov_b32_e32 v79, v43
	v_writelane_b32 v244, s1, 23
	v_cmp_le_u32_e64 s[0:1], v178, v5
	s_and_b64 s[0:1], vcc, s[0:1]
	v_cmp_gt_u32_e32 vcc, v19, v54
	v_writelane_b32 v244, s0, 24
	v_add_u32_e32 v19, 0x81, v147
	v_add_u32_e32 v180, -8, v44
	v_writelane_b32 v244, s1, 25
	v_cmp_le_u32_e64 s[0:1], v147, v54
	s_and_b64 s[0:1], vcc, s[0:1]
	v_cmp_gt_u32_e32 vcc, v19, v54
	v_writelane_b32 v244, s0, 26
	v_lshl_or_b32 v181, v44, 7, v140
	v_mov_b32_e32 v183, 0x358637bd
	v_writelane_b32 v244, s1, 27
	v_cmp_le_u32_e64 s[0:1], v19, v5
	s_and_b64 s[0:1], vcc, s[0:1]
	v_add_u32_e32 v19, 0x82, v147
	v_writelane_b32 v244, s0, 28
	v_cmp_gt_u32_e32 vcc, v19, v54
	v_add_u32_e32 v184, v137, v3
	v_writelane_b32 v244, s1, 29
	v_cmp_le_u32_e64 s[0:1], v19, v5
	s_and_b64 s[0:1], vcc, s[0:1]
	v_add_u32_e32 v19, 0x83, v147
	v_writelane_b32 v244, s0, 30
	v_cmp_gt_u32_e32 vcc, v19, v54
	v_add_u32_e32 v185, v7, v6
	v_writelane_b32 v244, s1, 31
	v_cmp_le_u32_e64 s[0:1], v19, v5
	v_add_u32_e32 v19, 0x90, v147
	s_and_b64 s[34:35], vcc, s[0:1]
	v_cmp_gt_u32_e32 vcc, v19, v54
	v_cmp_le_u32_e64 s[0:1], v19, v5
	v_add_u32_e32 v19, 0x91, v147
	s_and_b64 s[20:21], vcc, s[0:1]
	v_cmp_gt_u32_e32 vcc, v19, v54
	v_cmp_le_u32_e64 s[0:1], v19, v5
	v_add_u32_e32 v19, 0x92, v147
	s_and_b64 s[22:23], vcc, s[0:1]
	v_cmp_gt_u32_e32 vcc, v19, v54
	v_cmp_le_u32_e64 s[0:1], v19, v5
	v_add_u32_e32 v19, 0x93, v147
	s_and_b64 s[2:3], vcc, s[0:1]
	v_cmp_le_u32_e64 s[0:1], v19, v5
	v_or_b32_e32 v5, v147, v18
	v_mad_u32_u24 v18, v5, s6, v1
	v_mov_b32_e32 v5, v43
	v_lshl_add_u64 v[56:57], s[54:55], 0, v[4:5]
	v_readlane_b32 s44, v246, 38
	v_readlane_b32 s48, v246, 42
	v_readlane_b32 s49, v246, 43
	v_cmp_gt_u32_e32 vcc, v19, v54
	v_readlane_b32 s50, v246, 44
	v_readlane_b32 s51, v246, 45
	s_mov_b64 s[12:13], s[48:49]
	s_and_b64 s[10:11], vcc, s[0:1]
	s_mov_b64 s[14:15], s[50:51]
	v_lshl_add_u64 v[22:23], s[18:19], 0, v[4:5]
	s_mov_b64 s[0:1], 0x190cc000
	v_lshl_add_u64 v[58:59], s[14:15], 0, v[20:21]
	v_lshl_add_u64 v[60:61], s[12:13], 0, v[20:21]
	v_lshl_add_u64 v[62:63], v[22:23], 0, s[0:1]
	v_lshl_add_u64 v[20:21], s[16:17], 0, v[20:21]
	s_mov_b64 s[0:1], 0x8600000
	v_lshl_add_u64 v[64:65], v[20:21], 0, s[0:1]
	s_add_u32 s0, s18, 0x95a4000
	s_addc_u32 s1, s19, 0
	s_add_u32 s8, s18, 0xb6a4000
	s_addc_u32 s9, s19, 0
	v_writelane_b32 v244, s0, 32
	s_add_u32 s12, s18, 0xd7a4000
	s_addc_u32 s13, s19, 0
	v_writelane_b32 v244, s1, 33
	v_lshl_add_u64 v[4:5], s[16:17], 0, v[4:5]
	s_mov_b64 s[0:1], 0x9e00000
	v_lshl_add_u64 v[66:67], v[4:5], 0, s[0:1]
	s_add_u32 s0, s18, 0xf8a4000
	s_addc_u32 s1, s19, 0
	v_writelane_b32 v244, s0, 34
	v_mov_b32_e32 v1, v43
	v_lshl_add_u64 v[4:5], s[18:19], 0, v[0:1]
	v_writelane_b32 v244, s1, 35
	s_add_u32 s0, s18, 0x119a4400
	s_addc_u32 s1, s19, 0
	v_writelane_b32 v244, s0, 36
	v_add_u32_e32 v186, v8, v9
	s_mov_b32 s33, 0x3fb8aa3b
	v_writelane_b32 v244, s1, 37
	v_writelane_b32 v244, s8, 38
	s_add_u32 s0, s18, 0x15ba4000
	v_lshlrev_b32_e32 v82, 1, v42
	v_writelane_b32 v244, s9, 39
	v_writelane_b32 v244, s12, 40
	v_lshl_add_u64 v[68:69], s[8:9], 0, v[0:1]
	v_add_u32_e32 v187, v11, v10
	v_writelane_b32 v244, s13, 41
	v_writelane_b32 v244, s0, 42
	s_addc_u32 s0, s19, 0
	v_writelane_b32 v244, s0, 43
	s_mov_b64 s[0:1], 0x8524000
	v_lshl_add_u64 v[72:73], v[4:5], 0, s[0:1]
	s_mov_b64 s[0:1], 0x8d64000
	v_lshl_add_u64 v[74:75], v[4:5], 0, s[0:1]
	s_add_u32 s0, s16, 0x8e00000
	s_addc_u32 s1, s17, 0
	v_writelane_b32 v244, s0, 44
	v_lshlrev_b32_e32 v4, 4, v17
	v_mov_b32_e32 v5, v43
	v_writelane_b32 v244, s1, 45
	s_add_u32 s0, s16, 0x9600000
	s_addc_u32 s1, s17, 0
	v_writelane_b32 v244, s0, 46
	v_lshl_add_u64 v[70:71], s[12:13], 0, v[0:1]
	v_mul_lo_u32 v1, v44, s6
	v_writelane_b32 v244, s1, 47
	s_add_u32 s0, s18, 0x6424000
	s_addc_u32 s1, s19, 0
	s_add_u32 s8, s18, 0x119a4000
	s_addc_u32 s9, s19, 0
	v_writelane_b32 v244, s8, 48
	v_add3_u32 v182, v1, v0, s5
	v_mbcnt_lo_u32_b32 v0, -1, 0
	v_writelane_b32 v244, s9, 49
	v_writelane_b32 v244, s0, 50
	v_mbcnt_hi_u32_b32 v193, -1, v0
	v_and_b32_e32 v0, 64, v193
	v_writelane_b32 v244, s1, 51
	v_lshl_add_u64 v[80:81], s[0:1], 0, v[4:5]
	s_bfe_u32 s0, s30, 0x40003
	s_lshl_b32 s0, s0, 8
	s_add_i32 s30, s30, s0
	s_add_i32 s0, s30, 0xfffffe00
	s_bitcmp1_b32 s30, 0
	v_writelane_b32 v244, s0, 52
	s_cselect_b64 s[0:1], -1, 0
	v_writelane_b32 v244, s0, 54
	v_lshl_add_u64 v[76:77], s[8:9], 0, v[42:43]
	s_mov_b32 s17, 0
	v_writelane_b32 v244, s1, 55
	v_readlane_b32 s0, v246, 1
	v_readlane_b32 s1, v246, 2
	s_bitcmp1_b32 s0, 0
	s_cselect_b64 s[0:1], -1, 0
	v_writelane_b32 v244, s0, 56
	v_add_u32_e32 v188, v12, v6
	v_lshlrev_b32_e32 v84, 1, v2
	v_add_u32_e32 v189, v141, v13
	v_add_u32_e32 v190, v141, v14
	v_add_u32_e32 v191, v15, v10
	v_add_u32_e32 v192, v18, v6
	v_add_u32_e32 v194, 64, v0
	v_xor_b32_e32 v195, 1, v193
	v_xor_b32_e32 v196, 2, v193
	v_xor_b32_e32 v197, 4, v193
	v_xor_b32_e32 v198, 8, v193
	v_xor_b32_e32 v199, 16, v193
	v_xor_b32_e32 v200, 32, v193
	v_mov_b32_e32 v201, 0x42800000
	v_add_u32_e32 v203, 0x800, v133
	v_add_u32_e32 v204, 0x808, v133
	v_add_u32_e32 v205, 0x810, v133
	v_add_u32_e32 v206, 0x818, v133
	v_add_u32_e32 v207, 0x820, v133
	v_add_u32_e32 v208, 0x828, v133
	v_add_u32_e32 v209, 0x830, v133
	v_add_u32_e32 v210, 0x838, v133
	v_mov_b32_e32 v211, 0xf149f2ca
	s_mov_b32 s6, s30
	v_readlane_b32 s45, v246, 39
	v_readlane_b32 s46, v246, 40
	v_readlane_b32 s47, v246, 41
	v_readlane_b32 s52, v246, 46
	v_readlane_b32 s53, v246, 47
	v_readlane_b32 s54, v246, 48
	v_readlane_b32 s55, v246, 49
	v_readlane_b32 s56, v246, 50
	v_readlane_b32 s57, v246, 51
	v_readlane_b32 s58, v246, 52
	v_readlane_b32 s59, v246, 53
	v_writelane_b32 v244, s1, 57
	s_branch .LBB0_539

.Lp2_nowrap:
	s_nop 0
	v_writelane_b32 v244, s1, 52
	v_readlane_b32 s0, v244, 54
	v_readlane_b32 s4, v244, 56
	v_readlane_b32 s1, v244, 55
	v_readlane_b32 s5, v244, 57
	s_xor_b64 s[0:1], s[0:1], s[4:5]
	v_readlane_b32 s4, v246, 60
	v_writelane_b32 v244, s0, 54
	v_writelane_b32 v244, s1, 55
	s_bfe_u32 s5, s4, 0x40003
	s_lshl_b32 s5, s5, 8
	s_add_i32 s4, s4, s5
	s_cmp_lg_u32 s6, s4
	s_cbranch_scc0 .LBB0_576
